# ff2a->ff1b grid barrier replaced: buffer-reuse dependency only, ff1b starts at once and waits for the arrival counter before its first epilogue store
# speedup vs baseline: 1.0026x; 1.0026x over previous
.LBB0_789:
	s_mov_b32 s32, 0
	v_readlane_b32 s8, v254, 39
	v_readlane_b32 s9, v254, 40
	s_cmp_gt_i32 s9, 10
	s_cselect_b64 s[8:9], -1, 0
	s_and_b64 s[6:7], s[6:7], s[8:9]
	s_andn2_b64 vcc, exec, s[6:7]
	s_cbranch_vccnz .LBB0_843
	s_waitcnt vmcnt(0)
	s_barrier
	s_mov_b32 s32, 1
	s_mov_b64 s[6:7], exec
	v_readlane_b32 s10, v254, 2
	v_readlane_b32 s11, v254, 3
	s_nop 1
	s_and_b64 s[10:11], s[6:7], s[10:11]
	s_mov_b64 exec, s[10:11]
	s_cbranch_execz .Lff1b_arrive_join
	s_getreg_b32 s12, hwreg(HW_REG_XCC_ID, 0, 4)
	v_mov_b32_e32 v2, 0x23fc0
	ds_read_b64 v[2:3], v2
	s_lshl_b32 s12, s12, 6
	s_add_u32 s14, s62, 0x409000
	s_addc_u32 s15, s63, 0
	v_mov_b32_e32 v4, s12
	v_mov_b32_e32 v5, 1
	global_atomic_add v6, v4, v5, s[14:15] sc0
	s_waitcnt vmcnt(0) lgkmcnt(0)
	v_add_u32_e32 v6, 1, v6
	v_cmp_eq_u32_e32 vcc, v6, v2
	s_cbranch_vccz .Lff1b_arrive_join
	v_mov_b32_e32 v4, 0x400
	global_atomic_add v4, v5, s[14:15]
.Lff1b_arrive_join:
	s_mov_b64 exec, s[6:7]

.LBB0_860:
	s_cmp_eq_u32 s32, 0
	s_cbranch_scc1 .Lff1b_nowait
	s_mov_b32 s32, 0
	v_writelane_b32 v255, s4, 40
	v_writelane_b32 v255, s5, 41
	v_writelane_b32 v255, s26, 42
	v_writelane_b32 v255, s27, 43
	v_writelane_b32 v255, s46, 44
	v_writelane_b32 v255, s47, 45
	s_mov_b64 s[4:5], exec
	v_readlane_b32 s26, v254, 2
	v_readlane_b32 s27, v254, 3
	s_nop 1
	s_and_b64 s[26:27], s[4:5], s[26:27]
	s_mov_b64 exec, s[26:27]
	s_cbranch_execz .Lff1b_wait_join
	v_mov_b32_e32 v168, 0x23fc4
	ds_read_b32 v169, v168
	s_add_u32 s46, s62, 0x409000
	s_addc_u32 s47, s63, 0
	v_mov_b32_e32 v168, 0x400
	s_mov_b32 s26, 0
.Lff1b_spin:
	global_load_dword v170, v168, s[46:47] sc1
	s_waitcnt vmcnt(0) lgkmcnt(0)
	v_cmp_ge_u32_e32 vcc, v170, v169
	s_cbranch_vccnz .Lff1b_wait_join
	s_sleep 1
	s_add_u32 s26, s26, 1
	s_cmp_lt_u32 s26, 0x100000
	s_cbranch_scc1 .Lff1b_spin
.Lff1b_wait_join:
	s_mov_b64 exec, s[4:5]
	v_readlane_b32 s4, v255, 40
	v_readlane_b32 s5, v255, 41
	v_readlane_b32 s26, v255, 42
	v_readlane_b32 s27, v255, 43
	v_readlane_b32 s46, v255, 44
	v_readlane_b32 s47, v255, 45
	s_barrier
